# plus forget-logit tile epilogue: log-sigmoid via compensated hardware exp2/log2 in f32 (~17 VALU per element instead of ~110), same stores
# speedup vs baseline: 1.0285x; 1.0016x over previous
;     __device__ __forceinline__ void operator()(const f32x4 (&acc)[2][2][4][2], const Unit& u, int wr, int wc, int fr, int fq) const {
;     ...
;         } else {
;             if (wc == 0 && fq == 0) {
;                 const f32x4 b0 = *(const f32x4*)b_forget, b1 = *(const f32x4*)(b_forget + 4);
; #pragma unroll
;                 for (int ai = 0; ai < 2; ++ai)
; #pragma unroll
;                     for (int m = 0; m < 4; ++m) { const int row = row0 + ai * HALF + m * 16; const int rr = samp ? row - MP : row;
;                         f32x4 v0 = acc[ai][0][m][0] + b0, v1 = acc[ai][0][m][1] + b1;
; #pragma unroll
;                         for (int i = 0; i < 4; ++i) { v0[i] = fminf(v0[i], 0.f) - log1pf(expf(-fabsf(v0[i]))); v1[i] = fminf(v1[i], 0.f) - log1pf(expf(-fabsf(v1[i]))); }
;                         *(f32x4*)(logf_ws + (size_t)row * 8) = v0; *(f32x4*)(logf_ws + (size_t)row * 8 + 4) = v1;
;                         float* p = out + (samp ? O_LFS : O_LFP) + (size_t)rr * 8; *(f32x4*)p = v0; *(f32x4*)(p + 4) = v1; }
.LBB0_107:
	s_lshl_b32 s37, s12, 8
	s_cmp_gt_i32 s12, 63
	v_add_u32_e32 v164, s37, v176
	s_cselect_b64 s[8:9], -1, 0
	s_cmp_gt_i32 s15, 23
	s_mov_b64 s[0:1], -1
	s_cbranch_scc0 .LBB0_115
	s_cmp_gt_u32 s15, 39
	s_cbranch_scc0 .LBB0_112
	v_readlane_b32 s22, v250, 12
	v_readlane_b32 s23, v250, 13
	s_and_saveexec_b64 s[0:1], s[22:23]
	s_cbranch_execz .LBB0_111
	global_load_dwordx4 v[166:169], v155, s[46:47]
	global_load_dwordx4 v[170:173], v155, s[46:47] offset:16
	s_and_b64 s[24:25], s[8:9], exec
	s_mov_b32 s24, 0x18ca0000
	s_cselect_b32 s24, s24, 0x18400000
	v_readlane_b32 s74, v250, 4
	v_readlane_b32 s75, v250, 5
	v_readlane_b32 s22, v251, 58
	v_readlane_b32 s23, v251, 59
	s_mov_b32 s69, 0x3fb8aa3b
	s_mov_b32 s70, 0x32a57060
	s_mov_b32 s71, 0x3f317218
	s_nop 2
	s_add_u32 s60, s74, s24
	s_addc_u32 s61, s75, 0
	v_add_u32_e32 v132, 0xffffc000, v164
	v_cndmask_b32_e64 v132, v164, v132, s[8:9]
	v_lshlrev_b32_e32 v133, 5, v164
	v_lshlrev_b32_e32 v134, 5, v132
	s_waitcnt vmcnt(0)
	v_add_f32_e32 v204, v126, v166
	v_add_f32_e32 v209, v127, v167
	v_add_f32_e32 v214, v128, v168
	v_add_f32_e32 v219, v129, v169
	v_mul_f32_e64 v205, -|v204|, s69
	v_mul_f32_e64 v210, -|v209|, s69
	v_mul_f32_e64 v215, -|v214|, s69
	v_mul_f32_e64 v220, -|v219|, s69
	v_fma_f32 v206, -|v204|, s69, -v205
	v_fma_f32 v211, -|v209|, s69, -v210
	v_fma_f32 v216, -|v214|, s69, -v215
	v_fma_f32 v221, -|v219|, s69, -v220
	v_fma_f32 v206, -|v204|, s70, v206
	v_fma_f32 v211, -|v209|, s70, v211
	v_fma_f32 v216, -|v214|, s70, v216
	v_fma_f32 v221, -|v219|, s70, v221
	v_exp_f32_e32 v205, v205
	v_exp_f32_e32 v210, v210
	v_exp_f32_e32 v215, v215
	v_exp_f32_e32 v220, v220
	v_mul_f32_e32 v206, s71, v206
	v_mul_f32_e32 v211, s71, v211
	v_mul_f32_e32 v216, s71, v216
	v_mul_f32_e32 v221, s71, v221
	v_fma_f32 v205, v205, v206, v205
	v_fma_f32 v210, v210, v211, v210
	v_fma_f32 v215, v215, v216, v215
	v_fma_f32 v220, v220, v221, v220
	v_add_f32_e32 v207, 1.0, v205
	v_add_f32_e32 v212, 1.0, v210
	v_add_f32_e32 v217, 1.0, v215
	v_add_f32_e32 v130, 1.0, v220
	v_add_f32_e32 v208, -1.0, v207
	v_add_f32_e32 v213, -1.0, v212
	v_add_f32_e32 v218, -1.0, v217
	v_add_f32_e32 v131, -1.0, v130
	v_sub_f32_e32 v208, v205, v208
	v_sub_f32_e32 v213, v210, v213
	v_sub_f32_e32 v218, v215, v218
	v_sub_f32_e32 v131, v220, v131
	v_log_f32_e32 v206, v207
	v_log_f32_e32 v211, v212
	v_log_f32_e32 v216, v217
	v_log_f32_e32 v221, v130
	v_rcp_f32_e32 v207, v207
	v_rcp_f32_e32 v212, v212
	v_rcp_f32_e32 v217, v217
	v_rcp_f32_e32 v130, v130
	v_mul_f32_e32 v206, s71, v206
	v_mul_f32_e32 v211, s71, v211
	v_mul_f32_e32 v216, s71, v216
	v_mul_f32_e32 v221, s71, v221
	v_mul_f32_e32 v208, v208, v207
	v_mul_f32_e32 v213, v213, v212
	v_mul_f32_e32 v218, v218, v217
	v_mul_f32_e32 v131, v131, v130
	v_add_f32_e32 v206, v206, v208
	v_add_f32_e32 v211, v211, v213
	v_add_f32_e32 v216, v216, v218
	v_add_f32_e32 v221, v221, v131
	v_min_f32_e32 v204, 0, v204
	v_min_f32_e32 v209, 0, v209
	v_min_f32_e32 v214, 0, v214
	v_min_f32_e32 v219, 0, v219
	v_sub_f32_e32 v196, v204, v206
	v_sub_f32_e32 v197, v209, v211
	v_sub_f32_e32 v198, v214, v216
	v_sub_f32_e32 v199, v219, v221
	v_add_f32_e32 v204, v122, v170
	v_add_f32_e32 v209, v123, v171
	v_add_f32_e32 v214, v124, v172
	v_add_f32_e32 v219, v125, v173
	v_mul_f32_e64 v205, -|v204|, s69
	v_mul_f32_e64 v210, -|v209|, s69
	v_mul_f32_e64 v215, -|v214|, s69
	v_mul_f32_e64 v220, -|v219|, s69
	v_fma_f32 v206, -|v204|, s69, -v205
	v_fma_f32 v211, -|v209|, s69, -v210
	v_fma_f32 v216, -|v214|, s69, -v215
	v_fma_f32 v221, -|v219|, s69, -v220
	v_fma_f32 v206, -|v204|, s70, v206
	v_fma_f32 v211, -|v209|, s70, v211
	v_fma_f32 v216, -|v214|, s70, v216
	v_fma_f32 v221, -|v219|, s70, v221
	v_exp_f32_e32 v205, v205
	v_exp_f32_e32 v210, v210
	v_exp_f32_e32 v215, v215
	v_exp_f32_e32 v220, v220
	v_mul_f32_e32 v206, s71, v206
	v_mul_f32_e32 v211, s71, v211
	v_mul_f32_e32 v216, s71, v216
	v_mul_f32_e32 v221, s71, v221
	v_fma_f32 v205, v205, v206, v205
	v_fma_f32 v210, v210, v211, v210
	v_fma_f32 v215, v215, v216, v215
	v_fma_f32 v220, v220, v221, v220
	v_add_f32_e32 v207, 1.0, v205
	v_add_f32_e32 v212, 1.0, v210
	v_add_f32_e32 v217, 1.0, v215
	v_add_f32_e32 v130, 1.0, v220
	v_add_f32_e32 v208, -1.0, v207
	v_add_f32_e32 v213, -1.0, v212
	v_add_f32_e32 v218, -1.0, v217
	v_add_f32_e32 v131, -1.0, v130
	v_sub_f32_e32 v208, v205, v208
	v_sub_f32_e32 v213, v210, v213
	v_sub_f32_e32 v218, v215, v218
	v_sub_f32_e32 v131, v220, v131
	v_log_f32_e32 v206, v207
	v_log_f32_e32 v211, v212
	v_log_f32_e32 v216, v217
	v_log_f32_e32 v221, v130
	v_rcp_f32_e32 v207, v207
	v_rcp_f32_e32 v212, v212
	v_rcp_f32_e32 v217, v217
	v_rcp_f32_e32 v130, v130
	v_mul_f32_e32 v206, s71, v206
	v_mul_f32_e32 v211, s71, v211
	v_mul_f32_e32 v216, s71, v216
	v_mul_f32_e32 v221, s71, v221
	v_mul_f32_e32 v208, v208, v207
	v_mul_f32_e32 v213, v213, v212
	v_mul_f32_e32 v218, v218, v217
	v_mul_f32_e32 v131, v131, v130
	v_add_f32_e32 v206, v206, v208
	v_add_f32_e32 v211, v211, v213
	v_add_f32_e32 v216, v216, v218
	v_add_f32_e32 v221, v221, v131
	v_min_f32_e32 v204, 0, v204
	v_min_f32_e32 v209, 0, v209
	v_min_f32_e32 v214, 0, v214
	v_min_f32_e32 v219, 0, v219
	v_sub_f32_e32 v200, v204, v206
	v_sub_f32_e32 v201, v209, v211
	v_sub_f32_e32 v202, v214, v216
	v_sub_f32_e32 v203, v219, v221
	v_mov_b32_e32 v135, v133
	v_mov_b32_e32 v136, v134
	global_store_dwordx4 v135, v[196:199], s[22:23]
	global_store_dwordx4 v135, v[200:203], s[22:23] offset:16
	global_store_dwordx4 v136, v[196:199], s[60:61]
	global_store_dwordx4 v136, v[200:203], s[60:61] offset:16
	v_add_f32_e32 v204, v110, v166
	v_add_f32_e32 v209, v111, v167
	v_add_f32_e32 v214, v112, v168
	v_add_f32_e32 v219, v113, v169
;     __device__ __forceinline__ void operator()(const f32x4 (&acc)[2][2][4][2], const Unit& u, int wr, int wc, int fr, int fq) const {
;     ...
;                     for (int m = 0; m < 4; ++m) { const int row = row0 + ai * HALF + m * 16; const int rr = samp ? row - MP : row;
;                         f32x4 v0 = acc[ai][0][m][0] + b0, v1 = acc[ai][0][m][1] + b1;
; #pragma unroll
;                         for (int i = 0; i < 4; ++i) { v0[i] = fminf(v0[i], 0.f) - log1pf(expf(-fabsf(v0[i]))); v1[i] = fminf(v1[i], 0.f) - log1pf(expf(-fabsf(v1[i]))); }
;                         *(f32x4*)(logf_ws + (size_t)row * 8) = v0; *(f32x4*)(logf_ws + (size_t)row * 8 + 4) = v1;
;                         float* p = out + (samp ? O_LFS : O_LFP) + (size_t)rr * 8; *(f32x4*)p = v0; *(f32x4*)(p + 4) = v1; }
	v_mul_f32_e64 v205, -|v204|, s69
	v_mul_f32_e64 v210, -|v209|, s69
	v_mul_f32_e64 v215, -|v214|, s69
	v_mul_f32_e64 v220, -|v219|, s69
	v_fma_f32 v206, -|v204|, s69, -v205
	v_fma_f32 v211, -|v209|, s69, -v210
	v_fma_f32 v216, -|v214|, s69, -v215
	v_fma_f32 v221, -|v219|, s69, -v220
	v_fma_f32 v206, -|v204|, s70, v206
	v_fma_f32 v211, -|v209|, s70, v211
	v_fma_f32 v216, -|v214|, s70, v216
	v_fma_f32 v221, -|v219|, s70, v221
	v_exp_f32_e32 v205, v205
	v_exp_f32_e32 v210, v210
	v_exp_f32_e32 v215, v215
	v_exp_f32_e32 v220, v220
	v_mul_f32_e32 v206, s71, v206
	v_mul_f32_e32 v211, s71, v211
	v_mul_f32_e32 v216, s71, v216
	v_mul_f32_e32 v221, s71, v221
	v_fma_f32 v205, v205, v206, v205
	v_fma_f32 v210, v210, v211, v210
	v_fma_f32 v215, v215, v216, v215
	v_fma_f32 v220, v220, v221, v220
	v_add_f32_e32 v207, 1.0, v205
	v_add_f32_e32 v212, 1.0, v210
	v_add_f32_e32 v217, 1.0, v215
	v_add_f32_e32 v130, 1.0, v220
	v_add_f32_e32 v208, -1.0, v207
	v_add_f32_e32 v213, -1.0, v212
	v_add_f32_e32 v218, -1.0, v217
	v_add_f32_e32 v131, -1.0, v130
	v_sub_f32_e32 v208, v205, v208
	v_sub_f32_e32 v213, v210, v213
	v_sub_f32_e32 v218, v215, v218
	v_sub_f32_e32 v131, v220, v131
	v_log_f32_e32 v206, v207
	v_log_f32_e32 v211, v212
	v_log_f32_e32 v216, v217
	v_log_f32_e32 v221, v130
	v_rcp_f32_e32 v207, v207
	v_rcp_f32_e32 v212, v212
	v_rcp_f32_e32 v217, v217
	v_rcp_f32_e32 v130, v130
	v_mul_f32_e32 v206, s71, v206
	v_mul_f32_e32 v211, s71, v211
	v_mul_f32_e32 v216, s71, v216
	v_mul_f32_e32 v221, s71, v221
	v_mul_f32_e32 v208, v208, v207
	v_mul_f32_e32 v213, v213, v212
	v_mul_f32_e32 v218, v218, v217
	v_mul_f32_e32 v131, v131, v130
	v_add_f32_e32 v206, v206, v208
	v_add_f32_e32 v211, v211, v213
	v_add_f32_e32 v216, v216, v218
	v_add_f32_e32 v221, v221, v131
	v_min_f32_e32 v204, 0, v204
	v_min_f32_e32 v209, 0, v209
	v_min_f32_e32 v214, 0, v214
	v_min_f32_e32 v219, 0, v219
	v_sub_f32_e32 v196, v204, v206
	v_sub_f32_e32 v197, v209, v211
	v_sub_f32_e32 v198, v214, v216
	v_sub_f32_e32 v199, v219, v221
	v_add_f32_e32 v204, v106, v170
	v_add_f32_e32 v209, v107, v171
	v_add_f32_e32 v214, v108, v172
	v_add_f32_e32 v219, v109, v173
	v_mul_f32_e64 v205, -|v204|, s69
	v_mul_f32_e64 v210, -|v209|, s69
	v_mul_f32_e64 v215, -|v214|, s69
	v_mul_f32_e64 v220, -|v219|, s69
	v_fma_f32 v206, -|v204|, s69, -v205
	v_fma_f32 v211, -|v209|, s69, -v210
	v_fma_f32 v216, -|v214|, s69, -v215
	v_fma_f32 v221, -|v219|, s69, -v220
	v_fma_f32 v206, -|v204|, s70, v206
	v_fma_f32 v211, -|v209|, s70, v211
	v_fma_f32 v216, -|v214|, s70, v216
	v_fma_f32 v221, -|v219|, s70, v221
	v_exp_f32_e32 v205, v205
	v_exp_f32_e32 v210, v210
	v_exp_f32_e32 v215, v215
	v_exp_f32_e32 v220, v220
	v_mul_f32_e32 v206, s71, v206
	v_mul_f32_e32 v211, s71, v211
	v_mul_f32_e32 v216, s71, v216
	v_mul_f32_e32 v221, s71, v221
	v_fma_f32 v205, v205, v206, v205
	v_fma_f32 v210, v210, v211, v210
	v_fma_f32 v215, v215, v216, v215
	v_fma_f32 v220, v220, v221, v220
	v_add_f32_e32 v207, 1.0, v205
	v_add_f32_e32 v212, 1.0, v210
	v_add_f32_e32 v217, 1.0, v215
	v_add_f32_e32 v130, 1.0, v220
	v_add_f32_e32 v208, -1.0, v207
	v_add_f32_e32 v213, -1.0, v212
	v_add_f32_e32 v218, -1.0, v217
	v_add_f32_e32 v131, -1.0, v130
	v_sub_f32_e32 v208, v205, v208
	v_sub_f32_e32 v213, v210, v213
	v_sub_f32_e32 v218, v215, v218
	v_sub_f32_e32 v131, v220, v131
	v_log_f32_e32 v206, v207
	v_log_f32_e32 v211, v212
	v_log_f32_e32 v216, v217
	v_log_f32_e32 v221, v130
	v_rcp_f32_e32 v207, v207
	v_rcp_f32_e32 v212, v212
	v_rcp_f32_e32 v217, v217
	v_rcp_f32_e32 v130, v130
	v_mul_f32_e32 v206, s71, v206
	v_mul_f32_e32 v211, s71, v211
	v_mul_f32_e32 v216, s71, v216
	v_mul_f32_e32 v221, s71, v221
	v_mul_f32_e32 v208, v208, v207
	v_mul_f32_e32 v213, v213, v212
	v_mul_f32_e32 v218, v218, v217
	v_mul_f32_e32 v131, v131, v130
	v_add_f32_e32 v206, v206, v208
	v_add_f32_e32 v211, v211, v213
	v_add_f32_e32 v216, v216, v218
	v_add_f32_e32 v221, v221, v131
	v_min_f32_e32 v204, 0, v204
	v_min_f32_e32 v209, 0, v209
	v_min_f32_e32 v214, 0, v214
	v_min_f32_e32 v219, 0, v219
	v_sub_f32_e32 v200, v204, v206
	v_sub_f32_e32 v201, v209, v211
	v_sub_f32_e32 v202, v214, v216
	v_sub_f32_e32 v203, v219, v221
	v_add_u32_e32 v135, 0x200, v133
	v_add_u32_e32 v136, 0x200, v134
	global_store_dwordx4 v135, v[196:199], s[22:23]
	global_store_dwordx4 v135, v[200:203], s[22:23] offset:16
	global_store_dwordx4 v136, v[196:199], s[60:61]
	global_store_dwordx4 v136, v[200:203], s[60:61] offset:16
	v_add_f32_e32 v204, v94, v166
	v_add_f32_e32 v209, v95, v167
	v_add_f32_e32 v214, v96, v168
	v_add_f32_e32 v219, v97, v169
	v_mul_f32_e64 v205, -|v204|, s69
	v_mul_f32_e64 v210, -|v209|, s69
	v_mul_f32_e64 v215, -|v214|, s69
	v_mul_f32_e64 v220, -|v219|, s69
	v_fma_f32 v206, -|v204|, s69, -v205
	v_fma_f32 v211, -|v209|, s69, -v210
	v_fma_f32 v216, -|v214|, s69, -v215
	v_fma_f32 v221, -|v219|, s69, -v220
	v_fma_f32 v206, -|v204|, s70, v206
	v_fma_f32 v211, -|v209|, s70, v211
	v_fma_f32 v216, -|v214|, s70, v216
	v_fma_f32 v221, -|v219|, s70, v221
	v_exp_f32_e32 v205, v205
	v_exp_f32_e32 v210, v210
	v_exp_f32_e32 v215, v215
	v_exp_f32_e32 v220, v220
	v_mul_f32_e32 v206, s71, v206
	v_mul_f32_e32 v211, s71, v211
	v_mul_f32_e32 v216, s71, v216
	v_mul_f32_e32 v221, s71, v221
	v_fma_f32 v205, v205, v206, v205
	v_fma_f32 v210, v210, v211, v210
	v_fma_f32 v215, v215, v216, v215
	v_fma_f32 v220, v220, v221, v220
	v_add_f32_e32 v207, 1.0, v205
	v_add_f32_e32 v212, 1.0, v210
	v_add_f32_e32 v217, 1.0, v215
	v_add_f32_e32 v130, 1.0, v220
	v_add_f32_e32 v208, -1.0, v207
	v_add_f32_e32 v213, -1.0, v212
	v_add_f32_e32 v218, -1.0, v217
	v_add_f32_e32 v131, -1.0, v130
	v_sub_f32_e32 v208, v205, v208
	v_sub_f32_e32 v213, v210, v213
;     __device__ __forceinline__ void operator()(const f32x4 (&acc)[2][2][4][2], const Unit& u, int wr, int wc, int fr, int fq) const {
;     ...
;                     for (int m = 0; m < 4; ++m) { const int row = row0 + ai * HALF + m * 16; const int rr = samp ? row - MP : row;
;                         f32x4 v0 = acc[ai][0][m][0] + b0, v1 = acc[ai][0][m][1] + b1;
; #pragma unroll
;                         for (int i = 0; i < 4; ++i) { v0[i] = fminf(v0[i], 0.f) - log1pf(expf(-fabsf(v0[i]))); v1[i] = fminf(v1[i], 0.f) - log1pf(expf(-fabsf(v1[i]))); }
;                         *(f32x4*)(logf_ws + (size_t)row * 8) = v0; *(f32x4*)(logf_ws + (size_t)row * 8 + 4) = v1;
;                         float* p = out + (samp ? O_LFS : O_LFP) + (size_t)rr * 8; *(f32x4*)p = v0; *(f32x4*)(p + 4) = v1; }
	v_sub_f32_e32 v218, v215, v218
	v_sub_f32_e32 v131, v220, v131
	v_log_f32_e32 v206, v207
	v_log_f32_e32 v211, v212
	v_log_f32_e32 v216, v217
	v_log_f32_e32 v221, v130
	v_rcp_f32_e32 v207, v207
	v_rcp_f32_e32 v212, v212
	v_rcp_f32_e32 v217, v217
	v_rcp_f32_e32 v130, v130
	v_mul_f32_e32 v206, s71, v206
	v_mul_f32_e32 v211, s71, v211
	v_mul_f32_e32 v216, s71, v216
	v_mul_f32_e32 v221, s71, v221
	v_mul_f32_e32 v208, v208, v207
	v_mul_f32_e32 v213, v213, v212
	v_mul_f32_e32 v218, v218, v217
	v_mul_f32_e32 v131, v131, v130
	v_add_f32_e32 v206, v206, v208
	v_add_f32_e32 v211, v211, v213
	v_add_f32_e32 v216, v216, v218
	v_add_f32_e32 v221, v221, v131
	v_min_f32_e32 v204, 0, v204
	v_min_f32_e32 v209, 0, v209
	v_min_f32_e32 v214, 0, v214
	v_min_f32_e32 v219, 0, v219
	v_sub_f32_e32 v196, v204, v206
	v_sub_f32_e32 v197, v209, v211
	v_sub_f32_e32 v198, v214, v216
	v_sub_f32_e32 v199, v219, v221
	v_add_f32_e32 v204, v90, v170
	v_add_f32_e32 v209, v91, v171
	v_add_f32_e32 v214, v92, v172
	v_add_f32_e32 v219, v93, v173
	v_mul_f32_e64 v205, -|v204|, s69
	v_mul_f32_e64 v210, -|v209|, s69
	v_mul_f32_e64 v215, -|v214|, s69
	v_mul_f32_e64 v220, -|v219|, s69
	v_fma_f32 v206, -|v204|, s69, -v205
	v_fma_f32 v211, -|v209|, s69, -v210
	v_fma_f32 v216, -|v214|, s69, -v215
	v_fma_f32 v221, -|v219|, s69, -v220
	v_fma_f32 v206, -|v204|, s70, v206
	v_fma_f32 v211, -|v209|, s70, v211
	v_fma_f32 v216, -|v214|, s70, v216
	v_fma_f32 v221, -|v219|, s70, v221
	v_exp_f32_e32 v205, v205
	v_exp_f32_e32 v210, v210
	v_exp_f32_e32 v215, v215
	v_exp_f32_e32 v220, v220
	v_mul_f32_e32 v206, s71, v206
	v_mul_f32_e32 v211, s71, v211
	v_mul_f32_e32 v216, s71, v216
	v_mul_f32_e32 v221, s71, v221
	v_fma_f32 v205, v205, v206, v205
	v_fma_f32 v210, v210, v211, v210
	v_fma_f32 v215, v215, v216, v215
	v_fma_f32 v220, v220, v221, v220
	v_add_f32_e32 v207, 1.0, v205
	v_add_f32_e32 v212, 1.0, v210
	v_add_f32_e32 v217, 1.0, v215
	v_add_f32_e32 v130, 1.0, v220
	v_add_f32_e32 v208, -1.0, v207
	v_add_f32_e32 v213, -1.0, v212
	v_add_f32_e32 v218, -1.0, v217
	v_add_f32_e32 v131, -1.0, v130
	v_sub_f32_e32 v208, v205, v208
	v_sub_f32_e32 v213, v210, v213
	v_sub_f32_e32 v218, v215, v218
	v_sub_f32_e32 v131, v220, v131
	v_log_f32_e32 v206, v207
	v_log_f32_e32 v211, v212
	v_log_f32_e32 v216, v217
	v_log_f32_e32 v221, v130
	v_rcp_f32_e32 v207, v207
	v_rcp_f32_e32 v212, v212
	v_rcp_f32_e32 v217, v217
	v_rcp_f32_e32 v130, v130
	v_mul_f32_e32 v206, s71, v206
	v_mul_f32_e32 v211, s71, v211
	v_mul_f32_e32 v216, s71, v216
	v_mul_f32_e32 v221, s71, v221
	v_mul_f32_e32 v208, v208, v207
	v_mul_f32_e32 v213, v213, v212
	v_mul_f32_e32 v218, v218, v217
	v_mul_f32_e32 v131, v131, v130
	v_add_f32_e32 v206, v206, v208
	v_add_f32_e32 v211, v211, v213
	v_add_f32_e32 v216, v216, v218
	v_add_f32_e32 v221, v221, v131
	v_min_f32_e32 v204, 0, v204
	v_min_f32_e32 v209, 0, v209
	v_min_f32_e32 v214, 0, v214
	v_min_f32_e32 v219, 0, v219
	v_sub_f32_e32 v200, v204, v206
	v_sub_f32_e32 v201, v209, v211
	v_sub_f32_e32 v202, v214, v216
	v_sub_f32_e32 v203, v219, v221
	v_add_u32_e32 v135, 0x400, v133
	v_add_u32_e32 v136, 0x400, v134
	global_store_dwordx4 v135, v[196:199], s[22:23]
	global_store_dwordx4 v135, v[200:203], s[22:23] offset:16
	global_store_dwordx4 v136, v[196:199], s[60:61]
	global_store_dwordx4 v136, v[200:203], s[60:61] offset:16
	v_add_f32_e32 v204, v78, v166
	v_add_f32_e32 v209, v79, v167
	v_add_f32_e32 v214, v80, v168
	v_add_f32_e32 v219, v81, v169
	v_mul_f32_e64 v205, -|v204|, s69
	v_mul_f32_e64 v210, -|v209|, s69
	v_mul_f32_e64 v215, -|v214|, s69
	v_mul_f32_e64 v220, -|v219|, s69
	v_fma_f32 v206, -|v204|, s69, -v205
	v_fma_f32 v211, -|v209|, s69, -v210
	v_fma_f32 v216, -|v214|, s69, -v215
	v_fma_f32 v221, -|v219|, s69, -v220
	v_fma_f32 v206, -|v204|, s70, v206
	v_fma_f32 v211, -|v209|, s70, v211
	v_fma_f32 v216, -|v214|, s70, v216
	v_fma_f32 v221, -|v219|, s70, v221
	v_exp_f32_e32 v205, v205
	v_exp_f32_e32 v210, v210
	v_exp_f32_e32 v215, v215
	v_exp_f32_e32 v220, v220
	v_mul_f32_e32 v206, s71, v206
	v_mul_f32_e32 v211, s71, v211
	v_mul_f32_e32 v216, s71, v216
	v_mul_f32_e32 v221, s71, v221
	v_fma_f32 v205, v205, v206, v205
	v_fma_f32 v210, v210, v211, v210
	v_fma_f32 v215, v215, v216, v215
	v_fma_f32 v220, v220, v221, v220
	v_add_f32_e32 v207, 1.0, v205
	v_add_f32_e32 v212, 1.0, v210
	v_add_f32_e32 v217, 1.0, v215
	v_add_f32_e32 v130, 1.0, v220
	v_add_f32_e32 v208, -1.0, v207
	v_add_f32_e32 v213, -1.0, v212
	v_add_f32_e32 v218, -1.0, v217
	v_add_f32_e32 v131, -1.0, v130
	v_sub_f32_e32 v208, v205, v208
	v_sub_f32_e32 v213, v210, v213
	v_sub_f32_e32 v218, v215, v218
	v_sub_f32_e32 v131, v220, v131
	v_log_f32_e32 v206, v207
	v_log_f32_e32 v211, v212
	v_log_f32_e32 v216, v217
	v_log_f32_e32 v221, v130
	v_rcp_f32_e32 v207, v207
	v_rcp_f32_e32 v212, v212
	v_rcp_f32_e32 v217, v217
	v_rcp_f32_e32 v130, v130
	v_mul_f32_e32 v206, s71, v206
	v_mul_f32_e32 v211, s71, v211
	v_mul_f32_e32 v216, s71, v216
	v_mul_f32_e32 v221, s71, v221
	v_mul_f32_e32 v208, v208, v207
	v_mul_f32_e32 v213, v213, v212
	v_mul_f32_e32 v218, v218, v217
	v_mul_f32_e32 v131, v131, v130
	v_add_f32_e32 v206, v206, v208
	v_add_f32_e32 v211, v211, v213
	v_add_f32_e32 v216, v216, v218
	v_add_f32_e32 v221, v221, v131
	v_min_f32_e32 v204, 0, v204
	v_min_f32_e32 v209, 0, v209
	v_min_f32_e32 v214, 0, v214
	v_min_f32_e32 v219, 0, v219
	v_sub_f32_e32 v196, v204, v206
	v_sub_f32_e32 v197, v209, v211
	v_sub_f32_e32 v198, v214, v216
	v_sub_f32_e32 v199, v219, v221
	v_add_f32_e32 v204, v74, v170
	v_add_f32_e32 v209, v75, v171
	v_add_f32_e32 v214, v76, v172
	v_add_f32_e32 v219, v77, v173
	v_mul_f32_e64 v205, -|v204|, s69
	v_mul_f32_e64 v210, -|v209|, s69
;     __device__ __forceinline__ void operator()(const f32x4 (&acc)[2][2][4][2], const Unit& u, int wr, int wc, int fr, int fq) const {
;     ...
;                     for (int m = 0; m < 4; ++m) { const int row = row0 + ai * HALF + m * 16; const int rr = samp ? row - MP : row;
;                         f32x4 v0 = acc[ai][0][m][0] + b0, v1 = acc[ai][0][m][1] + b1;
; #pragma unroll
;                         for (int i = 0; i < 4; ++i) { v0[i] = fminf(v0[i], 0.f) - log1pf(expf(-fabsf(v0[i]))); v1[i] = fminf(v1[i], 0.f) - log1pf(expf(-fabsf(v1[i]))); }
;                         *(f32x4*)(logf_ws + (size_t)row * 8) = v0; *(f32x4*)(logf_ws + (size_t)row * 8 + 4) = v1;
;                         float* p = out + (samp ? O_LFS : O_LFP) + (size_t)rr * 8; *(f32x4*)p = v0; *(f32x4*)(p + 4) = v1; }
	v_mul_f32_e64 v215, -|v214|, s69
	v_mul_f32_e64 v220, -|v219|, s69
	v_fma_f32 v206, -|v204|, s69, -v205
	v_fma_f32 v211, -|v209|, s69, -v210
	v_fma_f32 v216, -|v214|, s69, -v215
	v_fma_f32 v221, -|v219|, s69, -v220
	v_fma_f32 v206, -|v204|, s70, v206
	v_fma_f32 v211, -|v209|, s70, v211
	v_fma_f32 v216, -|v214|, s70, v216
	v_fma_f32 v221, -|v219|, s70, v221
	v_exp_f32_e32 v205, v205
	v_exp_f32_e32 v210, v210
	v_exp_f32_e32 v215, v215
	v_exp_f32_e32 v220, v220
	v_mul_f32_e32 v206, s71, v206
	v_mul_f32_e32 v211, s71, v211
	v_mul_f32_e32 v216, s71, v216
	v_mul_f32_e32 v221, s71, v221
	v_fma_f32 v205, v205, v206, v205
	v_fma_f32 v210, v210, v211, v210
	v_fma_f32 v215, v215, v216, v215
	v_fma_f32 v220, v220, v221, v220
	v_add_f32_e32 v207, 1.0, v205
	v_add_f32_e32 v212, 1.0, v210
	v_add_f32_e32 v217, 1.0, v215
	v_add_f32_e32 v130, 1.0, v220
	v_add_f32_e32 v208, -1.0, v207
	v_add_f32_e32 v213, -1.0, v212
	v_add_f32_e32 v218, -1.0, v217
	v_add_f32_e32 v131, -1.0, v130
	v_sub_f32_e32 v208, v205, v208
	v_sub_f32_e32 v213, v210, v213
	v_sub_f32_e32 v218, v215, v218
	v_sub_f32_e32 v131, v220, v131
	v_log_f32_e32 v206, v207
	v_log_f32_e32 v211, v212
	v_log_f32_e32 v216, v217
	v_log_f32_e32 v221, v130
	v_rcp_f32_e32 v207, v207
	v_rcp_f32_e32 v212, v212
	v_rcp_f32_e32 v217, v217
	v_rcp_f32_e32 v130, v130
	v_mul_f32_e32 v206, s71, v206
	v_mul_f32_e32 v211, s71, v211
	v_mul_f32_e32 v216, s71, v216
	v_mul_f32_e32 v221, s71, v221
	v_mul_f32_e32 v208, v208, v207
	v_mul_f32_e32 v213, v213, v212
	v_mul_f32_e32 v218, v218, v217
	v_mul_f32_e32 v131, v131, v130
	v_add_f32_e32 v206, v206, v208
	v_add_f32_e32 v211, v211, v213
	v_add_f32_e32 v216, v216, v218
	v_add_f32_e32 v221, v221, v131
	v_min_f32_e32 v204, 0, v204
	v_min_f32_e32 v209, 0, v209
	v_min_f32_e32 v214, 0, v214
	v_min_f32_e32 v219, 0, v219
	v_sub_f32_e32 v200, v204, v206
	v_sub_f32_e32 v201, v209, v211
	v_sub_f32_e32 v202, v214, v216
	v_sub_f32_e32 v203, v219, v221
	v_add_u32_e32 v135, 0x600, v133
	v_add_u32_e32 v136, 0x600, v134
	global_store_dwordx4 v135, v[196:199], s[22:23]
	global_store_dwordx4 v135, v[200:203], s[22:23] offset:16
	global_store_dwordx4 v136, v[196:199], s[60:61]
	global_store_dwordx4 v136, v[200:203], s[60:61] offset:16
	v_add_f32_e32 v204, v62, v166
	v_add_f32_e32 v209, v63, v167
	v_add_f32_e32 v214, v64, v168
	v_add_f32_e32 v219, v65, v169
	v_mul_f32_e64 v205, -|v204|, s69
	v_mul_f32_e64 v210, -|v209|, s69
	v_mul_f32_e64 v215, -|v214|, s69
	v_mul_f32_e64 v220, -|v219|, s69
	v_fma_f32 v206, -|v204|, s69, -v205
	v_fma_f32 v211, -|v209|, s69, -v210
	v_fma_f32 v216, -|v214|, s69, -v215
	v_fma_f32 v221, -|v219|, s69, -v220
	v_fma_f32 v206, -|v204|, s70, v206
	v_fma_f32 v211, -|v209|, s70, v211
	v_fma_f32 v216, -|v214|, s70, v216
	v_fma_f32 v221, -|v219|, s70, v221
	v_exp_f32_e32 v205, v205
	v_exp_f32_e32 v210, v210
	v_exp_f32_e32 v215, v215
	v_exp_f32_e32 v220, v220
	v_mul_f32_e32 v206, s71, v206
	v_mul_f32_e32 v211, s71, v211
	v_mul_f32_e32 v216, s71, v216
	v_mul_f32_e32 v221, s71, v221
	v_fma_f32 v205, v205, v206, v205
	v_fma_f32 v210, v210, v211, v210
	v_fma_f32 v215, v215, v216, v215
	v_fma_f32 v220, v220, v221, v220
	v_add_f32_e32 v207, 1.0, v205
	v_add_f32_e32 v212, 1.0, v210
	v_add_f32_e32 v217, 1.0, v215
	v_add_f32_e32 v130, 1.0, v220
	v_add_f32_e32 v208, -1.0, v207
	v_add_f32_e32 v213, -1.0, v212
	v_add_f32_e32 v218, -1.0, v217
	v_add_f32_e32 v131, -1.0, v130
	v_sub_f32_e32 v208, v205, v208
	v_sub_f32_e32 v213, v210, v213
	v_sub_f32_e32 v218, v215, v218
	v_sub_f32_e32 v131, v220, v131
	v_log_f32_e32 v206, v207
	v_log_f32_e32 v211, v212
	v_log_f32_e32 v216, v217
	v_log_f32_e32 v221, v130
	v_rcp_f32_e32 v207, v207
	v_rcp_f32_e32 v212, v212
	v_rcp_f32_e32 v217, v217
	v_rcp_f32_e32 v130, v130
	v_mul_f32_e32 v206, s71, v206
	v_mul_f32_e32 v211, s71, v211
	v_mul_f32_e32 v216, s71, v216
	v_mul_f32_e32 v221, s71, v221
	v_mul_f32_e32 v208, v208, v207
	v_mul_f32_e32 v213, v213, v212
	v_mul_f32_e32 v218, v218, v217
	v_mul_f32_e32 v131, v131, v130
	v_add_f32_e32 v206, v206, v208
	v_add_f32_e32 v211, v211, v213
	v_add_f32_e32 v216, v216, v218
	v_add_f32_e32 v221, v221, v131
	v_min_f32_e32 v204, 0, v204
	v_min_f32_e32 v209, 0, v209
	v_min_f32_e32 v214, 0, v214
	v_min_f32_e32 v219, 0, v219
	v_sub_f32_e32 v196, v204, v206
	v_sub_f32_e32 v197, v209, v211
	v_sub_f32_e32 v198, v214, v216
	v_sub_f32_e32 v199, v219, v221
	v_add_f32_e32 v204, v58, v170
	v_add_f32_e32 v209, v59, v171
	v_add_f32_e32 v214, v60, v172
	v_add_f32_e32 v219, v61, v173
	v_mul_f32_e64 v205, -|v204|, s69
	v_mul_f32_e64 v210, -|v209|, s69
	v_mul_f32_e64 v215, -|v214|, s69
	v_mul_f32_e64 v220, -|v219|, s69
	v_fma_f32 v206, -|v204|, s69, -v205
	v_fma_f32 v211, -|v209|, s69, -v210
	v_fma_f32 v216, -|v214|, s69, -v215
	v_fma_f32 v221, -|v219|, s69, -v220
	v_fma_f32 v206, -|v204|, s70, v206
	v_fma_f32 v211, -|v209|, s70, v211
	v_fma_f32 v216, -|v214|, s70, v216
	v_fma_f32 v221, -|v219|, s70, v221
	v_exp_f32_e32 v205, v205
	v_exp_f32_e32 v210, v210
	v_exp_f32_e32 v215, v215
	v_exp_f32_e32 v220, v220
	v_mul_f32_e32 v206, s71, v206
	v_mul_f32_e32 v211, s71, v211
	v_mul_f32_e32 v216, s71, v216
	v_mul_f32_e32 v221, s71, v221
	v_fma_f32 v205, v205, v206, v205
	v_fma_f32 v210, v210, v211, v210
	v_fma_f32 v215, v215, v216, v215
	v_fma_f32 v220, v220, v221, v220
	v_add_f32_e32 v207, 1.0, v205
	v_add_f32_e32 v212, 1.0, v210
	v_add_f32_e32 v217, 1.0, v215
	v_add_f32_e32 v130, 1.0, v220
	v_add_f32_e32 v208, -1.0, v207
	v_add_f32_e32 v213, -1.0, v212
	v_add_f32_e32 v218, -1.0, v217
	v_add_f32_e32 v131, -1.0, v130
	v_sub_f32_e32 v208, v205, v208
	v_sub_f32_e32 v213, v210, v213
	v_sub_f32_e32 v218, v215, v218
	v_sub_f32_e32 v131, v220, v131
;     __device__ __forceinline__ void operator()(const f32x4 (&acc)[2][2][4][2], const Unit& u, int wr, int wc, int fr, int fq) const {
;     ...
;                     for (int m = 0; m < 4; ++m) { const int row = row0 + ai * HALF + m * 16; const int rr = samp ? row - MP : row;
;                         f32x4 v0 = acc[ai][0][m][0] + b0, v1 = acc[ai][0][m][1] + b1;
; #pragma unroll
;                         for (int i = 0; i < 4; ++i) { v0[i] = fminf(v0[i], 0.f) - log1pf(expf(-fabsf(v0[i]))); v1[i] = fminf(v1[i], 0.f) - log1pf(expf(-fabsf(v1[i]))); }
;                         *(f32x4*)(logf_ws + (size_t)row * 8) = v0; *(f32x4*)(logf_ws + (size_t)row * 8 + 4) = v1;
;                         float* p = out + (samp ? O_LFS : O_LFP) + (size_t)rr * 8; *(f32x4*)p = v0; *(f32x4*)(p + 4) = v1; }
	v_log_f32_e32 v206, v207
	v_log_f32_e32 v211, v212
	v_log_f32_e32 v216, v217
	v_log_f32_e32 v221, v130
	v_rcp_f32_e32 v207, v207
	v_rcp_f32_e32 v212, v212
	v_rcp_f32_e32 v217, v217
	v_rcp_f32_e32 v130, v130
	v_mul_f32_e32 v206, s71, v206
	v_mul_f32_e32 v211, s71, v211
	v_mul_f32_e32 v216, s71, v216
	v_mul_f32_e32 v221, s71, v221
	v_mul_f32_e32 v208, v208, v207
	v_mul_f32_e32 v213, v213, v212
	v_mul_f32_e32 v218, v218, v217
	v_mul_f32_e32 v131, v131, v130
	v_add_f32_e32 v206, v206, v208
	v_add_f32_e32 v211, v211, v213
	v_add_f32_e32 v216, v216, v218
	v_add_f32_e32 v221, v221, v131
	v_min_f32_e32 v204, 0, v204
	v_min_f32_e32 v209, 0, v209
	v_min_f32_e32 v214, 0, v214
	v_min_f32_e32 v219, 0, v219
	v_sub_f32_e32 v200, v204, v206
	v_sub_f32_e32 v201, v209, v211
	v_sub_f32_e32 v202, v214, v216
	v_sub_f32_e32 v203, v219, v221
	v_add_u32_e32 v135, 0x1000, v133
	v_add_u32_e32 v136, 0x1000, v134
	global_store_dwordx4 v135, v[196:199], s[22:23]
	global_store_dwordx4 v135, v[200:203], s[22:23] offset:16
	global_store_dwordx4 v136, v[196:199], s[60:61]
	global_store_dwordx4 v136, v[200:203], s[60:61] offset:16
	v_add_f32_e32 v204, v46, v166
	v_add_f32_e32 v209, v47, v167
	v_add_f32_e32 v214, v48, v168
	v_add_f32_e32 v219, v49, v169
	v_mul_f32_e64 v205, -|v204|, s69
	v_mul_f32_e64 v210, -|v209|, s69
	v_mul_f32_e64 v215, -|v214|, s69
	v_mul_f32_e64 v220, -|v219|, s69
	v_fma_f32 v206, -|v204|, s69, -v205
	v_fma_f32 v211, -|v209|, s69, -v210
	v_fma_f32 v216, -|v214|, s69, -v215
	v_fma_f32 v221, -|v219|, s69, -v220
	v_fma_f32 v206, -|v204|, s70, v206
	v_fma_f32 v211, -|v209|, s70, v211
	v_fma_f32 v216, -|v214|, s70, v216
	v_fma_f32 v221, -|v219|, s70, v221
	v_exp_f32_e32 v205, v205
	v_exp_f32_e32 v210, v210
	v_exp_f32_e32 v215, v215
	v_exp_f32_e32 v220, v220
	v_mul_f32_e32 v206, s71, v206
	v_mul_f32_e32 v211, s71, v211
	v_mul_f32_e32 v216, s71, v216
	v_mul_f32_e32 v221, s71, v221
	v_fma_f32 v205, v205, v206, v205
	v_fma_f32 v210, v210, v211, v210
	v_fma_f32 v215, v215, v216, v215
	v_fma_f32 v220, v220, v221, v220
	v_add_f32_e32 v207, 1.0, v205
	v_add_f32_e32 v212, 1.0, v210
	v_add_f32_e32 v217, 1.0, v215
	v_add_f32_e32 v130, 1.0, v220
	v_add_f32_e32 v208, -1.0, v207
	v_add_f32_e32 v213, -1.0, v212
	v_add_f32_e32 v218, -1.0, v217
	v_add_f32_e32 v131, -1.0, v130
	v_sub_f32_e32 v208, v205, v208
	v_sub_f32_e32 v213, v210, v213
	v_sub_f32_e32 v218, v215, v218
	v_sub_f32_e32 v131, v220, v131
	v_log_f32_e32 v206, v207
	v_log_f32_e32 v211, v212
	v_log_f32_e32 v216, v217
	v_log_f32_e32 v221, v130
	v_rcp_f32_e32 v207, v207
	v_rcp_f32_e32 v212, v212
	v_rcp_f32_e32 v217, v217
	v_rcp_f32_e32 v130, v130
	v_mul_f32_e32 v206, s71, v206
	v_mul_f32_e32 v211, s71, v211
	v_mul_f32_e32 v216, s71, v216
	v_mul_f32_e32 v221, s71, v221
	v_mul_f32_e32 v208, v208, v207
	v_mul_f32_e32 v213, v213, v212
	v_mul_f32_e32 v218, v218, v217
	v_mul_f32_e32 v131, v131, v130
	v_add_f32_e32 v206, v206, v208
	v_add_f32_e32 v211, v211, v213
	v_add_f32_e32 v216, v216, v218
	v_add_f32_e32 v221, v221, v131
	v_min_f32_e32 v204, 0, v204
	v_min_f32_e32 v209, 0, v209
	v_min_f32_e32 v214, 0, v214
	v_min_f32_e32 v219, 0, v219
	v_sub_f32_e32 v196, v204, v206
	v_sub_f32_e32 v197, v209, v211
	v_sub_f32_e32 v198, v214, v216
	v_sub_f32_e32 v199, v219, v221
	v_add_f32_e32 v204, v42, v170
	v_add_f32_e32 v209, v43, v171
	v_add_f32_e32 v214, v44, v172
	v_add_f32_e32 v219, v45, v173
	v_mul_f32_e64 v205, -|v204|, s69
	v_mul_f32_e64 v210, -|v209|, s69
	v_mul_f32_e64 v215, -|v214|, s69
	v_mul_f32_e64 v220, -|v219|, s69
	v_fma_f32 v206, -|v204|, s69, -v205
	v_fma_f32 v211, -|v209|, s69, -v210
	v_fma_f32 v216, -|v214|, s69, -v215
	v_fma_f32 v221, -|v219|, s69, -v220
	v_fma_f32 v206, -|v204|, s70, v206
	v_fma_f32 v211, -|v209|, s70, v211
	v_fma_f32 v216, -|v214|, s70, v216
	v_fma_f32 v221, -|v219|, s70, v221
	v_exp_f32_e32 v205, v205
	v_exp_f32_e32 v210, v210
	v_exp_f32_e32 v215, v215
	v_exp_f32_e32 v220, v220
	v_mul_f32_e32 v206, s71, v206
	v_mul_f32_e32 v211, s71, v211
	v_mul_f32_e32 v216, s71, v216
	v_mul_f32_e32 v221, s71, v221
	v_fma_f32 v205, v205, v206, v205
	v_fma_f32 v210, v210, v211, v210
	v_fma_f32 v215, v215, v216, v215
	v_fma_f32 v220, v220, v221, v220
	v_add_f32_e32 v207, 1.0, v205
	v_add_f32_e32 v212, 1.0, v210
	v_add_f32_e32 v217, 1.0, v215
	v_add_f32_e32 v130, 1.0, v220
	v_add_f32_e32 v208, -1.0, v207
	v_add_f32_e32 v213, -1.0, v212
	v_add_f32_e32 v218, -1.0, v217
	v_add_f32_e32 v131, -1.0, v130
	v_sub_f32_e32 v208, v205, v208
	v_sub_f32_e32 v213, v210, v213
	v_sub_f32_e32 v218, v215, v218
	v_sub_f32_e32 v131, v220, v131
	v_log_f32_e32 v206, v207
	v_log_f32_e32 v211, v212
	v_log_f32_e32 v216, v217
	v_log_f32_e32 v221, v130
	v_rcp_f32_e32 v207, v207
	v_rcp_f32_e32 v212, v212
	v_rcp_f32_e32 v217, v217
	v_rcp_f32_e32 v130, v130
	v_mul_f32_e32 v206, s71, v206
	v_mul_f32_e32 v211, s71, v211
	v_mul_f32_e32 v216, s71, v216
	v_mul_f32_e32 v221, s71, v221
	v_mul_f32_e32 v208, v208, v207
	v_mul_f32_e32 v213, v213, v212
	v_mul_f32_e32 v218, v218, v217
	v_mul_f32_e32 v131, v131, v130
	v_add_f32_e32 v206, v206, v208
	v_add_f32_e32 v211, v211, v213
	v_add_f32_e32 v216, v216, v218
	v_add_f32_e32 v221, v221, v131
	v_min_f32_e32 v204, 0, v204
	v_min_f32_e32 v209, 0, v209
	v_min_f32_e32 v214, 0, v214
	v_min_f32_e32 v219, 0, v219
	v_sub_f32_e32 v200, v204, v206
	v_sub_f32_e32 v201, v209, v211
	v_sub_f32_e32 v202, v214, v216
	v_sub_f32_e32 v203, v219, v221
	v_add_u32_e32 v135, 0x1200, v133
	v_add_u32_e32 v136, 0x1200, v134
	global_store_dwordx4 v135, v[196:199], s[22:23]
	global_store_dwordx4 v135, v[200:203], s[22:23] offset:16
	global_store_dwordx4 v136, v[196:199], s[60:61]
	global_store_dwordx4 v136, v[200:203], s[60:61] offset:16
;     __device__ __forceinline__ void operator()(const f32x4 (&acc)[2][2][4][2], const Unit& u, int wr, int wc, int fr, int fq) const {
;     ...
;                     for (int m = 0; m < 4; ++m) { const int row = row0 + ai * HALF + m * 16; const int rr = samp ? row - MP : row;
;                         f32x4 v0 = acc[ai][0][m][0] + b0, v1 = acc[ai][0][m][1] + b1;
; #pragma unroll
;                         for (int i = 0; i < 4; ++i) { v0[i] = fminf(v0[i], 0.f) - log1pf(expf(-fabsf(v0[i]))); v1[i] = fminf(v1[i], 0.f) - log1pf(expf(-fabsf(v1[i]))); }
;                         *(f32x4*)(logf_ws + (size_t)row * 8) = v0; *(f32x4*)(logf_ws + (size_t)row * 8 + 4) = v1;
;                         float* p = out + (samp ? O_LFS : O_LFP) + (size_t)rr * 8; *(f32x4*)p = v0; *(f32x4*)(p + 4) = v1; }
	v_add_f32_e32 v204, v30, v166
	v_add_f32_e32 v209, v31, v167
	v_add_f32_e32 v214, v32, v168
	v_add_f32_e32 v219, v33, v169
	v_mul_f32_e64 v205, -|v204|, s69
	v_mul_f32_e64 v210, -|v209|, s69
	v_mul_f32_e64 v215, -|v214|, s69
	v_mul_f32_e64 v220, -|v219|, s69
	v_fma_f32 v206, -|v204|, s69, -v205
	v_fma_f32 v211, -|v209|, s69, -v210
	v_fma_f32 v216, -|v214|, s69, -v215
	v_fma_f32 v221, -|v219|, s69, -v220
	v_fma_f32 v206, -|v204|, s70, v206
	v_fma_f32 v211, -|v209|, s70, v211
	v_fma_f32 v216, -|v214|, s70, v216
	v_fma_f32 v221, -|v219|, s70, v221
	v_exp_f32_e32 v205, v205
	v_exp_f32_e32 v210, v210
	v_exp_f32_e32 v215, v215
	v_exp_f32_e32 v220, v220
	v_mul_f32_e32 v206, s71, v206
	v_mul_f32_e32 v211, s71, v211
	v_mul_f32_e32 v216, s71, v216
	v_mul_f32_e32 v221, s71, v221
	v_fma_f32 v205, v205, v206, v205
	v_fma_f32 v210, v210, v211, v210
	v_fma_f32 v215, v215, v216, v215
	v_fma_f32 v220, v220, v221, v220
	v_add_f32_e32 v207, 1.0, v205
	v_add_f32_e32 v212, 1.0, v210
	v_add_f32_e32 v217, 1.0, v215
	v_add_f32_e32 v130, 1.0, v220
	v_add_f32_e32 v208, -1.0, v207
	v_add_f32_e32 v213, -1.0, v212
	v_add_f32_e32 v218, -1.0, v217
	v_add_f32_e32 v131, -1.0, v130
	v_sub_f32_e32 v208, v205, v208
	v_sub_f32_e32 v213, v210, v213
	v_sub_f32_e32 v218, v215, v218
	v_sub_f32_e32 v131, v220, v131
	v_log_f32_e32 v206, v207
	v_log_f32_e32 v211, v212
	v_log_f32_e32 v216, v217
	v_log_f32_e32 v221, v130
	v_rcp_f32_e32 v207, v207
	v_rcp_f32_e32 v212, v212
	v_rcp_f32_e32 v217, v217
	v_rcp_f32_e32 v130, v130
	v_mul_f32_e32 v206, s71, v206
	v_mul_f32_e32 v211, s71, v211
	v_mul_f32_e32 v216, s71, v216
	v_mul_f32_e32 v221, s71, v221
	v_mul_f32_e32 v208, v208, v207
	v_mul_f32_e32 v213, v213, v212
	v_mul_f32_e32 v218, v218, v217
	v_mul_f32_e32 v131, v131, v130
	v_add_f32_e32 v206, v206, v208
	v_add_f32_e32 v211, v211, v213
	v_add_f32_e32 v216, v216, v218
	v_add_f32_e32 v221, v221, v131
	v_min_f32_e32 v204, 0, v204
	v_min_f32_e32 v209, 0, v209
	v_min_f32_e32 v214, 0, v214
	v_min_f32_e32 v219, 0, v219
	v_sub_f32_e32 v196, v204, v206
	v_sub_f32_e32 v197, v209, v211
	v_sub_f32_e32 v198, v214, v216
	v_sub_f32_e32 v199, v219, v221
	v_add_f32_e32 v204, v26, v170
	v_add_f32_e32 v209, v27, v171
	v_add_f32_e32 v214, v28, v172
	v_add_f32_e32 v219, v29, v173
	v_mul_f32_e64 v205, -|v204|, s69
	v_mul_f32_e64 v210, -|v209|, s69
	v_mul_f32_e64 v215, -|v214|, s69
	v_mul_f32_e64 v220, -|v219|, s69
	v_fma_f32 v206, -|v204|, s69, -v205
	v_fma_f32 v211, -|v209|, s69, -v210
	v_fma_f32 v216, -|v214|, s69, -v215
	v_fma_f32 v221, -|v219|, s69, -v220
	v_fma_f32 v206, -|v204|, s70, v206
	v_fma_f32 v211, -|v209|, s70, v211
	v_fma_f32 v216, -|v214|, s70, v216
	v_fma_f32 v221, -|v219|, s70, v221
	v_exp_f32_e32 v205, v205
	v_exp_f32_e32 v210, v210
	v_exp_f32_e32 v215, v215
	v_exp_f32_e32 v220, v220
	v_mul_f32_e32 v206, s71, v206
	v_mul_f32_e32 v211, s71, v211
	v_mul_f32_e32 v216, s71, v216
	v_mul_f32_e32 v221, s71, v221
	v_fma_f32 v205, v205, v206, v205
	v_fma_f32 v210, v210, v211, v210
	v_fma_f32 v215, v215, v216, v215
	v_fma_f32 v220, v220, v221, v220
	v_add_f32_e32 v207, 1.0, v205
	v_add_f32_e32 v212, 1.0, v210
	v_add_f32_e32 v217, 1.0, v215
	v_add_f32_e32 v130, 1.0, v220
	v_add_f32_e32 v208, -1.0, v207
	v_add_f32_e32 v213, -1.0, v212
	v_add_f32_e32 v218, -1.0, v217
	v_add_f32_e32 v131, -1.0, v130
	v_sub_f32_e32 v208, v205, v208
	v_sub_f32_e32 v213, v210, v213
	v_sub_f32_e32 v218, v215, v218
	v_sub_f32_e32 v131, v220, v131
	v_log_f32_e32 v206, v207
	v_log_f32_e32 v211, v212
	v_log_f32_e32 v216, v217
	v_log_f32_e32 v221, v130
	v_rcp_f32_e32 v207, v207
	v_rcp_f32_e32 v212, v212
	v_rcp_f32_e32 v217, v217
	v_rcp_f32_e32 v130, v130
	v_mul_f32_e32 v206, s71, v206
	v_mul_f32_e32 v211, s71, v211
	v_mul_f32_e32 v216, s71, v216
	v_mul_f32_e32 v221, s71, v221
	v_mul_f32_e32 v208, v208, v207
	v_mul_f32_e32 v213, v213, v212
	v_mul_f32_e32 v218, v218, v217
	v_mul_f32_e32 v131, v131, v130
	v_add_f32_e32 v206, v206, v208
	v_add_f32_e32 v211, v211, v213
	v_add_f32_e32 v216, v216, v218
	v_add_f32_e32 v221, v221, v131
	v_min_f32_e32 v204, 0, v204
	v_min_f32_e32 v209, 0, v209
	v_min_f32_e32 v214, 0, v214
	v_min_f32_e32 v219, 0, v219
	v_sub_f32_e32 v200, v204, v206
	v_sub_f32_e32 v201, v209, v211
	v_sub_f32_e32 v202, v214, v216
	v_sub_f32_e32 v203, v219, v221
	v_add_u32_e32 v135, 0x1400, v133
	v_add_u32_e32 v136, 0x1400, v134
	global_store_dwordx4 v135, v[196:199], s[22:23]
	global_store_dwordx4 v135, v[200:203], s[22:23] offset:16
	global_store_dwordx4 v136, v[196:199], s[60:61]
	global_store_dwordx4 v136, v[200:203], s[60:61] offset:16
;     __device__ __forceinline__ void operator()(const f32x4 (&acc)[2][2][4][2], const Unit& u, int wr, int wc, int fr, int fq) const {
;     ...
;                     for (int m = 0; m < 4; ++m) { const int row = row0 + ai * HALF + m * 16; const int rr = samp ? row - MP : row;
;                         f32x4 v0 = acc[ai][0][m][0] + b0, v1 = acc[ai][0][m][1] + b1;
; #pragma unroll
;                         for (int i = 0; i < 4; ++i) { v0[i] = fminf(v0[i], 0.f) - log1pf(expf(-fabsf(v0[i]))); v1[i] = fminf(v1[i], 0.f) - log1pf(expf(-fabsf(v1[i]))); }
;                         *(f32x4*)(logf_ws + (size_t)row * 8) = v0; *(f32x4*)(logf_ws + (size_t)row * 8 + 4) = v1;
;                         float* p = out + (samp ? O_LFS : O_LFP) + (size_t)rr * 8; *(f32x4*)p = v0; *(f32x4*)(p + 4) = v1; }
	v_add_f32_e32 v204, v14, v166
	v_add_f32_e32 v209, v15, v167
	v_add_f32_e32 v214, v16, v168
	v_add_f32_e32 v219, v17, v169
	v_mul_f32_e64 v205, -|v204|, s69
	v_mul_f32_e64 v210, -|v209|, s69
	v_mul_f32_e64 v215, -|v214|, s69
	v_mul_f32_e64 v220, -|v219|, s69
	v_fma_f32 v206, -|v204|, s69, -v205
	v_fma_f32 v211, -|v209|, s69, -v210
	v_fma_f32 v216, -|v214|, s69, -v215
	v_fma_f32 v221, -|v219|, s69, -v220
	v_fma_f32 v206, -|v204|, s70, v206
	v_fma_f32 v211, -|v209|, s70, v211
	v_fma_f32 v216, -|v214|, s70, v216
	v_fma_f32 v221, -|v219|, s70, v221
	v_exp_f32_e32 v205, v205
	v_exp_f32_e32 v210, v210
	v_exp_f32_e32 v215, v215
	v_exp_f32_e32 v220, v220
	v_mul_f32_e32 v206, s71, v206
	v_mul_f32_e32 v211, s71, v211
	v_mul_f32_e32 v216, s71, v216
	v_mul_f32_e32 v221, s71, v221
	v_fma_f32 v205, v205, v206, v205
	v_fma_f32 v210, v210, v211, v210
	v_fma_f32 v215, v215, v216, v215
	v_fma_f32 v220, v220, v221, v220
	v_add_f32_e32 v207, 1.0, v205
	v_add_f32_e32 v212, 1.0, v210
	v_add_f32_e32 v217, 1.0, v215
	v_add_f32_e32 v130, 1.0, v220
	v_add_f32_e32 v208, -1.0, v207
	v_add_f32_e32 v213, -1.0, v212
	v_add_f32_e32 v218, -1.0, v217
	v_add_f32_e32 v131, -1.0, v130
	v_sub_f32_e32 v208, v205, v208
	v_sub_f32_e32 v213, v210, v213
	v_sub_f32_e32 v218, v215, v218
	v_sub_f32_e32 v131, v220, v131
	v_log_f32_e32 v206, v207
	v_log_f32_e32 v211, v212
	v_log_f32_e32 v216, v217
	v_log_f32_e32 v221, v130
	v_rcp_f32_e32 v207, v207
	v_rcp_f32_e32 v212, v212
	v_rcp_f32_e32 v217, v217
	v_rcp_f32_e32 v130, v130
	v_mul_f32_e32 v206, s71, v206
	v_mul_f32_e32 v211, s71, v211
	v_mul_f32_e32 v216, s71, v216
	v_mul_f32_e32 v221, s71, v221
	v_mul_f32_e32 v208, v208, v207
	v_mul_f32_e32 v213, v213, v212
	v_mul_f32_e32 v218, v218, v217
	v_mul_f32_e32 v131, v131, v130
	v_add_f32_e32 v206, v206, v208
	v_add_f32_e32 v211, v211, v213
	v_add_f32_e32 v216, v216, v218
	v_add_f32_e32 v221, v221, v131
	v_min_f32_e32 v204, 0, v204
	v_min_f32_e32 v209, 0, v209
	v_min_f32_e32 v214, 0, v214
	v_min_f32_e32 v219, 0, v219
	v_sub_f32_e32 v196, v204, v206
	v_sub_f32_e32 v197, v209, v211
	v_sub_f32_e32 v198, v214, v216
	v_sub_f32_e32 v199, v219, v221
	v_add_f32_e32 v204, v10, v170
	v_add_f32_e32 v209, v11, v171
	v_add_f32_e32 v214, v12, v172
	v_add_f32_e32 v219, v13, v173
	v_mul_f32_e64 v205, -|v204|, s69
	v_mul_f32_e64 v210, -|v209|, s69
	v_mul_f32_e64 v215, -|v214|, s69
	v_mul_f32_e64 v220, -|v219|, s69
	v_fma_f32 v206, -|v204|, s69, -v205
	v_fma_f32 v211, -|v209|, s69, -v210
	v_fma_f32 v216, -|v214|, s69, -v215
	v_fma_f32 v221, -|v219|, s69, -v220
	v_fma_f32 v206, -|v204|, s70, v206
	v_fma_f32 v211, -|v209|, s70, v211
	v_fma_f32 v216, -|v214|, s70, v216
	v_fma_f32 v221, -|v219|, s70, v221
	v_exp_f32_e32 v205, v205
	v_exp_f32_e32 v210, v210
	v_exp_f32_e32 v215, v215
	v_exp_f32_e32 v220, v220
	v_mul_f32_e32 v206, s71, v206
	v_mul_f32_e32 v211, s71, v211
	v_mul_f32_e32 v216, s71, v216
	v_mul_f32_e32 v221, s71, v221
	v_fma_f32 v205, v205, v206, v205
	v_fma_f32 v210, v210, v211, v210
	v_fma_f32 v215, v215, v216, v215
	v_fma_f32 v220, v220, v221, v220
	v_add_f32_e32 v207, 1.0, v205
	v_add_f32_e32 v212, 1.0, v210
	v_add_f32_e32 v217, 1.0, v215
	v_add_f32_e32 v130, 1.0, v220
	v_add_f32_e32 v208, -1.0, v207
	v_add_f32_e32 v213, -1.0, v212
	v_add_f32_e32 v218, -1.0, v217
	v_add_f32_e32 v131, -1.0, v130
	v_sub_f32_e32 v208, v205, v208
	v_sub_f32_e32 v213, v210, v213
	v_sub_f32_e32 v218, v215, v218
	v_sub_f32_e32 v131, v220, v131
	v_log_f32_e32 v206, v207
	v_log_f32_e32 v211, v212
	v_log_f32_e32 v216, v217
	v_log_f32_e32 v221, v130
	v_rcp_f32_e32 v207, v207
	v_rcp_f32_e32 v212, v212
	v_rcp_f32_e32 v217, v217
	v_rcp_f32_e32 v130, v130
	v_mul_f32_e32 v206, s71, v206
	v_mul_f32_e32 v211, s71, v211
	v_mul_f32_e32 v216, s71, v216
	v_mul_f32_e32 v221, s71, v221
	v_mul_f32_e32 v208, v208, v207
	v_mul_f32_e32 v213, v213, v212
	v_mul_f32_e32 v218, v218, v217
	v_mul_f32_e32 v131, v131, v130
	v_add_f32_e32 v206, v206, v208
	v_add_f32_e32 v211, v211, v213
	v_add_f32_e32 v216, v216, v218
	v_add_f32_e32 v221, v221, v131
	v_min_f32_e32 v204, 0, v204
	v_min_f32_e32 v209, 0, v209
	v_min_f32_e32 v214, 0, v214
	v_min_f32_e32 v219, 0, v219
	v_sub_f32_e32 v200, v204, v206
	v_sub_f32_e32 v201, v209, v211
	v_sub_f32_e32 v202, v214, v216
	v_sub_f32_e32 v203, v219, v221
	v_add_u32_e32 v135, 0x1600, v133
	v_add_u32_e32 v136, 0x1600, v134
	global_store_dwordx4 v135, v[196:199], s[22:23]
	global_store_dwordx4 v135, v[200:203], s[22:23] offset:16
	global_store_dwordx4 v136, v[196:199], s[60:61]
	global_store_dwordx4 v136, v[200:203], s[60:61] offset:16
